# spatial-gating item output stores widened to dwordx4 via v_permlane16_swap, counted vmcnt waits between the stores recomputed for the smaller store count
# speedup vs baseline: 1.0086x; 1.0022x over previous
; #define LAS __attribute__((address_space(3)))
; #define OPQV(x) asm volatile("" : "+v"(x))
; DEV void sgu_item(LAS unsigned char* lds, const bf16_t* P, const bf16_t* VN, const float* sgu_w, const float* sgu_b, bf16_t* OC, int item) {
;     int tid = threadIdx.x; OPQV(tid); const int lane = tid & 63, wv = tid >> 6, fr = lane & 15, g4 = lane >> 4;
;     LAS bf16_t* VT = (LAS bf16_t*)lds;
;     const int g = item & 7, ch = (item >> 3) & 15, b = item >> 7;
;     const size_t tok0 = (size_t)b * S_ + ch * 128;
;     const int t = wv * 16 + fr;
;     const size_t tok = tok0 + t;
;     u32x4 vin[4];
; #pragma unroll
;     for (int it = 0; it < 4; ++it) { const int idx = it * 512 + tid, s = idx >> 4, c8 = (idx & 15) * 8; vin[it] = *(const u32x4*)(VN + (tok0 + s) * 1024 + g * 128 + c8); }
;     const float* wrow = sgu_w + ((size_t)g * 128 + t) * 128;
;     f32x4 wa[4], wb[4];
; #pragma unroll
;     for (int ks = 0; ks < 4; ++ks) { wa[ks] = *(const f32x4*)(wrow + ks * 32 + g4 * 8); wb[ks] = *(const f32x4*)(wrow + ks * 32 + g4 * 8 + 4); }
;     u32x2 uu[8];
; #pragma unroll
;     for (int n = 0; n < 8; ++n) uu[n] = *(const u32x2*)(P + tok * NP + COL_U + g * 128 + n * 16 + g4 * 4);
;     const float bias = sgu_b[g * 128 + t];
; #pragma unroll
;     for (int it = 0; it < 4; ++it) { const int idx = it * 512 + tid, s = idx >> 4, c8 = (idx & 15) * 8;
; #pragma unroll
;         for (int j = 0; j < 4; ++j) { VT[(c8 + 2 * j) * 136 + s] = (bf16_t)(vin[it][j] & 0xffffu); VT[(c8 + 2 * j + 1) * 136 + s] = (bf16_t)(vin[it][j] >> 16); } }
;     __syncthreads();
; DEV void phase_mix(LAS unsigned char* lds, const bf16_t* P, const bf16_t* QB, const bf16_t* KV, const bf16_t* KC, const bf16_t* VC, const float* rel_bias, bf16_t* OB,
;                    const bf16_t* VN, const float* sgu_w, const float* sgu_b, bf16_t* OC, int* ctr) {
;     ...
;     for (;;) {
;         if (tid == 0) *(LAS int*)(lds + AT_NEXT) = atomicAdd(ctr, 1);
;         __syncthreads();
;         const int i = *(const LAS int*)(lds + AT_NEXT);
;         __syncthreads();
;         if (i >= 2048) break;
;         if (i < 1024) attn_item(lds, P, QB, KV, KC, VC, rel_bias, OB, (i & 31) >> 2, i & 3, 31 - (i >> 5));
;         else sgu_item(lds, P, VN, sgu_w, sgu_b, OC, i - 1024);
.LBB0_164:
	s_or_b64 exec, exec, s[4:5]
	v_mov_b32_e32 v0, s95
	s_waitcnt lgkmcnt(0)
	s_barrier
	ds_read_b32 v0, v0
	s_movk_i32 s4, 0x7ff
	s_waitcnt lgkmcnt(0)
	s_barrier
	v_cmp_lt_i32_e32 vcc, s4, v0
	v_readfirstlane_b32 s43, v0
	s_mov_b64 s[4:5], -1
	s_cbranch_vccnz .LBB0_159
	s_cmpk_gt_i32 s43, 0x3ff
	s_cbranch_scc0 .LBB0_167
	s_add_i32 s4, s43, 0xfffffc00
	s_lshl_b32 s5, s4, 4
	s_lshl_b32 s4, s4, 7
	v_mov_b32_e32 v8, v210
	s_and_b32 s6, s4, 0x380
	s_and_b32 s36, s5, 0x3f80
	v_lshlrev_b32_e32 v0, 3, v8
	s_lshl_b32 s4, s6, 1
	v_and_b32_e32 v9, 0x78, v0
	s_add_u32 s44, s34, s4
	v_ashrrev_i32_e32 v4, 4, v8
	s_addc_u32 s45, s35, 0
	v_lshlrev_b32_e32 v0, 1, v9
	v_ashrrev_i32_e32 v5, 31, v4
	v_lshl_add_u64 v[2:3], s[44:45], 0, v[0:1]
	v_lshl_add_u64 v[6:7], v[4:5], 0, s[36:37]
	v_add_u32_e32 v0, 0x200, v8
	v_lshlrev_b64 v[6:7], 11, v[6:7]
	v_ashrrev_i32_e32 v70, 4, v0
	v_lshl_add_u64 v[6:7], v[2:3], 0, v[6:7]
	v_ashrrev_i32_e32 v71, 31, v70
	global_load_dwordx4 v[30:33], v[6:7], off
	v_lshl_add_u64 v[6:7], v[70:71], 0, s[36:37]
	v_add_u32_e32 v0, 0x400, v8
	v_lshlrev_b64 v[6:7], 11, v[6:7]
	v_ashrrev_i32_e32 v72, 4, v0
	v_lshl_add_u64 v[6:7], v[2:3], 0, v[6:7]
	v_ashrrev_i32_e32 v73, 31, v72
	global_load_dwordx4 v[34:37], v[6:7], off
	v_lshl_add_u64 v[6:7], v[72:73], 0, s[36:37]
	v_add_u32_e32 v0, 0x600, v8
	v_lshlrev_b64 v[6:7], 11, v[6:7]
	v_ashrrev_i32_e32 v74, 4, v0
	v_lshl_add_u64 v[6:7], v[2:3], 0, v[6:7]
	v_ashrrev_i32_e32 v75, 31, v74
	global_load_dwordx4 v[38:41], v[6:7], off
	v_lshl_add_u64 v[6:7], v[74:75], 0, s[36:37]
	v_ashrrev_i32_e32 v0, 2, v8
	v_lshlrev_b64 v[6:7], 11, v[6:7]
	s_waitcnt vmcnt(11)
	v_bfi_b32 v28, -16, v0, v8
	v_lshl_add_u64 v[2:3], v[2:3], 0, v[6:7]
	v_ashrrev_i32_e32 v29, 31, v28
	s_mov_b32 s7, s37
	global_load_dwordx4 v[42:45], v[2:3], off
	v_lshl_add_u64 v[2:3], v[28:29], 0, s[6:7]
	v_bfe_u32 v0, v8, 4, 2
	v_lshlrev_b64 v[2:3], 9, v[2:3]
	v_lshl_add_u64 v[2:3], s[80:81], 0, v[2:3]
	v_lshlrev_b32_e32 v6, 5, v0
	v_mov_b32_e32 v7, v1
	v_lshl_add_u64 v[6:7], v[2:3], 0, v[6:7]
	global_load_dwordx4 v[46:49], v[6:7], off
	global_load_dwordx4 v[50:53], v[6:7], off offset:16
	v_mov_b64_e32 v[2:3], s[76:77]
	v_and_b32_e32 v82, 15, v8
	v_add_u32_e32 v8, s6, v28
	s_movk_i32 s6, 0x110
	v_lshl_add_u64 v[24:25], v[28:29], 0, s[36:37]
	s_mov_b32 s5, s37
	v_mad_u32_u24 v71, v9, s6, 0
	v_ashrrev_i32_e32 v9, 31, v8
	v_mad_i64_i32 v[2:3], s[6:7], v24, s59, v[2:3]
	v_lshl_add_u32 v73, v4, 1, v71
	v_lshlrev_b32_e32 v0, 3, v0
	v_lshl_add_u64 v[4:5], v[8:9], 2, s[82:83]
	v_lshl_add_u64 v[2:3], v[2:3], 0, s[4:5]
	global_load_dword v29, v[4:5], off
	v_lshl_add_u64 v[10:11], v[2:3], 0, v[0:1]
	global_load_dwordx4 v[54:57], v[6:7], off offset:144
	global_load_dwordx4 v[58:61], v[6:7], off offset:128
	global_load_dwordx4 v[62:65], v[6:7], off offset:272
	global_load_dwordx4 v[66:69], v[6:7], off offset:256
	global_load_dwordx4 v[2:5], v[6:7], off offset:400
	s_nop 0
	global_load_dwordx4 v[6:9], v[6:7], off offset:384
	s_mov_b64 s[6:7], 0x2c00
	s_movk_i32 s5, 0x2000
	v_lshl_add_u64 v[76:77], v[10:11], 0, s[6:7]
	v_add_co_u32_e32 v10, vcc, s5, v10
	v_or_b32_e32 v90, 32, v0
	s_nop 0
	v_addc_co_u32_e32 v11, vcc, 0, v11, vcc
	global_load_dwordx2 v[22:23], v[76:77], off offset:32
	global_load_dwordx2 v[20:21], v[76:77], off offset:64
	global_load_dwordx2 v[18:19], v[76:77], off offset:96
	global_load_dwordx2 v[16:17], v[76:77], off offset:128
	global_load_dwordx2 v[26:27], v[10:11], off offset:3072
	global_load_dwordx2 v[14:15], v[76:77], off offset:160
	global_load_dwordx2 v[12:13], v[76:77], off offset:192
	s_nop 0
	global_load_dwordx2 v[10:11], v[76:77], off offset:224
	v_cmp_le_i32_e32 vcc, v0, v28
	v_or_b32_e32 v91, 33, v0
	s_movk_i32 s5, 0x88
	v_mad_u32_u24 v83, v82, s5, v227
	v_mad_u32_u24 v84, v82, s5, v252
	v_mad_u32_u24 v85, v82, s5, v216
	v_mad_u32_u24 v86, v82, s5, v217
	v_mad_u32_u24 v87, v82, s5, v218
	s_waitcnt vmcnt(20)
	ds_write_b16 v73, v30
	ds_write_b16_d16_hi v73, v30 offset:272
	ds_write_b16 v73, v31 offset:544
	ds_write_b16_d16_hi v73, v31 offset:816
	ds_write_b16 v73, v32 offset:1088
	ds_write_b16_d16_hi v73, v32 offset:1360
	ds_write_b16 v73, v33 offset:1632
	ds_write_b16_d16_hi v73, v33 offset:1904
	v_lshl_add_u32 v30, v70, 1, v71
	s_waitcnt vmcnt(19)
	ds_write_b16 v30, v34
	ds_write_b16_d16_hi v30, v34 offset:272
	ds_write_b16 v30, v35 offset:544
	ds_write_b16_d16_hi v30, v35 offset:816
	ds_write_b16 v30, v36 offset:1088
	ds_write_b16_d16_hi v30, v36 offset:1360
	ds_write_b16 v30, v37 offset:1632
	ds_write_b16_d16_hi v30, v37 offset:1904
	v_lshl_add_u32 v30, v72, 1, v71
	s_waitcnt vmcnt(18)
	ds_write_b16 v30, v38
	ds_write_b16_d16_hi v30, v38 offset:272
	ds_write_b16 v30, v39 offset:544
	ds_write_b16_d16_hi v30, v39 offset:816
	ds_write_b16 v30, v40 offset:1088
	ds_write_b16_d16_hi v30, v40 offset:1360
	ds_write_b16 v30, v41 offset:1632
	ds_write_b16_d16_hi v30, v41 offset:1904
	v_lshl_add_u32 v30, v74, 1, v71
	s_waitcnt vmcnt(17)
	ds_write_b16 v30, v42
	ds_write_b16_d16_hi v30, v42 offset:272
	ds_write_b16 v30, v43 offset:544
	ds_write_b16_d16_hi v30, v43 offset:816
	ds_write_b16 v30, v44 offset:1088
	ds_write_b16_d16_hi v30, v44 offset:1360
	ds_write_b16 v30, v45 offset:1632
	ds_write_b16_d16_hi v30, v45 offset:1904
	v_or_b32_e32 v32, 2, v0
	v_or_b32_e32 v33, 3, v0
	v_or_b32_e32 v34, 4, v0
	v_or_b32_e32 v35, 5, v0
	v_or_b32_e32 v36, 6, v0
	v_or_b32_e32 v37, 7, v0
	s_waitcnt vmcnt(16) lgkmcnt(0)
	v_cndmask_b32_e32 v30, 0, v46, vcc
	v_cmp_lt_i32_e32 vcc, v0, v28
	s_barrier
; #define LAS __attribute__((address_space(3)))
; DEV u32x4 pack8(const float (&f)[8]) { u32x4 w; w.x = cvt_pk_bf16(f[0], f[1]); w.y = cvt_pk_bf16(f[2], f[3]); w.z = cvt_pk_bf16(f[4], f[5]); w.w = cvt_pk_bf16(f[6], f[7]); return w; }
; DEV void sgu_item(LAS unsigned char* lds, const bf16_t* P, const bf16_t* VN, const float* sgu_w, const float* sgu_b, bf16_t* OC, int item) {
;     ...
; #pragma unroll
;     for (int ks = 0; ks < 4; ++ks) { const int s0 = ks * 32 + g4 * 8;
;         float wf[8] = {wa[ks][0], wa[ks][1], wa[ks][2], wa[ks][3], wb[ks][0], wb[ks][1], wb[ks][2], wb[ks][3]};
; #pragma unroll
;         for (int j = 0; j < 8; ++j) if (s0 + j > t) wf[j] = 0.f;
;         const bf16x8 wfr = as_bf16x8(pack8(wf));
; #pragma unroll
;         for (int n = 0; n < 8; ++n) { const bf16x8 vf = *(const LAS bf16x8*)(lds + ((n * 16 + fr) * 136 + s0) * 2);
;             acc[n] = __builtin_amdgcn_mfma_f32_16x16x32_bf16(vf, wfr, acc[n], 0, 0, 0); } }
	s_nop 0
	v_cndmask_b32_e32 v31, 0, v47, vcc
	v_cmp_le_i32_e32 vcc, v32, v28
	v_cvt_pk_bf16_f32 v30, v30, v31
	v_mad_u32_u24 v88, v82, s5, v219
	v_mad_u32_u24 v89, v82, s5, v220
	v_cndmask_b32_e32 v32, 0, v48, vcc
	v_cmp_le_i32_e32 vcc, v33, v28
	v_add_u32_e32 v38, v83, v0
	v_add_u32_e32 v42, v84, v0
	v_cndmask_b32_e32 v33, 0, v49, vcc
	v_cmp_le_i32_e32 vcc, v34, v28
	v_cvt_pk_bf16_f32 v31, v32, v33
	v_add_u32_e32 v46, v85, v0
	v_add_u32_e32 v70, v87, v0
	s_waitcnt vmcnt(15)
	v_cndmask_b32_e32 v34, 0, v50, vcc
	v_cmp_le_i32_e32 vcc, v35, v28
	v_add_u32_e32 v50, v86, v0
	v_add_u32_e32 v74, v88, v0
	v_cndmask_b32_e32 v35, 0, v51, vcc
	v_cmp_le_i32_e32 vcc, v36, v28
	v_cvt_pk_bf16_f32 v32, v34, v35
	v_mad_u32_u24 v34, v82, s5, v0
	v_lshl_add_u32 v34, v34, 1, 0
	v_cndmask_b32_e32 v36, 0, v52, vcc
	v_cmp_le_i32_e32 vcc, v37, v28
	v_add_u32_e32 v78, v89, v0
	v_lshl_add_u32 v38, v38, 1, 0
	v_cndmask_b32_e32 v37, 0, v53, vcc
	v_cmp_le_i32_e32 vcc, v90, v28
	v_cvt_pk_bf16_f32 v33, v36, v37
	ds_read_b128 v[34:37], v34
	ds_read_b128 v[38:41], v38
	s_waitcnt vmcnt(12)
	v_cndmask_b32_e32 v58, 0, v58, vcc
	v_cmp_le_i32_e32 vcc, v91, v28
	v_or_b32_e32 v91, 34, v0
	v_lshl_add_u32 v42, v42, 1, 0
	v_cndmask_b32_e32 v59, 0, v59, vcc
	v_cmp_le_i32_e32 vcc, v91, v28
	v_or_b32_e32 v91, 35, v0
	v_lshl_add_u32 v46, v46, 1, 0
	v_cndmask_b32_e32 v60, 0, v60, vcc
	v_cmp_le_i32_e32 vcc, v91, v28
	v_or_b32_e32 v91, 36, v0
	v_lshl_add_u32 v50, v50, 1, 0
	v_cndmask_b32_e32 v61, 0, v61, vcc
	v_cmp_le_i32_e32 vcc, v91, v28
	v_lshl_add_u32 v70, v70, 1, 0
	v_lshl_add_u32 v74, v74, 1, 0
	v_cndmask_b32_e32 v91, 0, v54, vcc
	v_or_b32_e32 v54, 37, v0
	v_cmp_le_i32_e32 vcc, v54, v28
	v_or_b32_e32 v54, 38, v0
	v_lshl_add_u32 v78, v78, 1, 0
	v_cndmask_b32_e32 v92, 0, v55, vcc
	v_cmp_le_i32_e32 vcc, v54, v28
	v_or_b32_e32 v54, 39, v0
	ds_read_b128 v[42:45], v42
	ds_read_b128 v[46:49], v46
	ds_read_b128 v[50:53], v50
	ds_read_b128 v[70:73], v70
	ds_read_b128 v[74:77], v74
	ds_read_b128 v[78:81], v78
	v_cndmask_b32_e32 v93, 0, v56, vcc
	v_cmp_le_i32_e32 vcc, v54, v28
	v_cvt_pk_bf16_f32 v54, v58, v59
	v_mad_u32_u24 v58, v82, s5, v90
	v_lshl_add_u32 v58, v58, 1, 0
	v_cndmask_b32_e32 v57, 0, v57, vcc
	v_cvt_pk_bf16_f32 v55, v60, v61
	v_cvt_pk_bf16_f32 v56, v91, v92
	v_cvt_pk_bf16_f32 v57, v93, v57
	ds_read_b128 v[58:61], v58
	s_waitcnt lgkmcnt(8)
	v_mfma_f32_16x16x32_bf16 v[34:37], v[34:37], v[30:33], 0
	v_lshlrev_b64 v[24:25], 11, v[24:25]
	v_lshl_add_u64 v[24:25], s[88:89], 0, v[24:25]
	s_waitcnt lgkmcnt(7)
	v_mfma_f32_16x16x32_bf16 v[38:41], v[38:41], v[30:33], 0
	s_waitcnt lgkmcnt(6)
	v_mfma_f32_16x16x32_bf16 v[42:45], v[42:45], v[30:33], 0
	s_waitcnt lgkmcnt(5)
	v_mfma_f32_16x16x32_bf16 v[46:49], v[46:49], v[30:33], 0
	s_waitcnt lgkmcnt(4)
	v_mfma_f32_16x16x32_bf16 v[50:53], v[50:53], v[30:33], 0
	s_waitcnt lgkmcnt(3)
	v_mfma_f32_16x16x32_bf16 v[70:73], v[70:73], v[30:33], 0
	s_waitcnt lgkmcnt(2)
	v_mfma_f32_16x16x32_bf16 v[74:77], v[74:77], v[30:33], 0
	s_waitcnt lgkmcnt(1)
	v_mfma_f32_16x16x32_bf16 v[30:33], v[78:81], v[30:33], 0
	v_add_u32_e32 v78, v90, v83
	v_lshl_add_u32 v78, v78, 1, 0
	ds_read_b128 v[78:81], v78
	s_waitcnt lgkmcnt(1)
	v_mfma_f32_16x16x32_bf16 v[34:37], v[58:61], v[54:57], v[34:37]
	v_add_u32_e32 v58, v90, v84
	v_lshl_add_u32 v58, v58, 1, 0
	ds_read_b128 v[58:61], v58
	s_waitcnt lgkmcnt(1)
	v_mfma_f32_16x16x32_bf16 v[38:41], v[78:81], v[54:57], v[38:41]
	v_add_u32_e32 v78, v90, v85
	v_lshl_add_u32 v78, v78, 1, 0
	ds_read_b128 v[78:81], v78
	s_waitcnt lgkmcnt(1)
	v_mfma_f32_16x16x32_bf16 v[42:45], v[58:61], v[54:57], v[42:45]
	v_add_u32_e32 v58, v90, v86
	v_lshl_add_u32 v58, v58, 1, 0
	ds_read_b128 v[58:61], v58
	s_waitcnt lgkmcnt(1)
	v_mfma_f32_16x16x32_bf16 v[46:49], v[78:81], v[54:57], v[46:49]
	v_add_u32_e32 v78, v90, v87
	v_lshl_add_u32 v78, v78, 1, 0
	ds_read_b128 v[78:81], v78
	s_waitcnt lgkmcnt(1)
	v_mfma_f32_16x16x32_bf16 v[50:53], v[58:61], v[54:57], v[50:53]
	v_add_u32_e32 v58, v90, v88
	v_lshl_add_u32 v58, v58, 1, 0
	ds_read_b128 v[58:61], v58
	s_waitcnt lgkmcnt(1)
	v_mfma_f32_16x16x32_bf16 v[70:73], v[78:81], v[54:57], v[70:73]
	v_add_u32_e32 v78, v90, v89
	v_lshl_add_u32 v78, v78, 1, 0
	ds_read_b128 v[78:81], v78
	s_waitcnt lgkmcnt(1)
	v_mfma_f32_16x16x32_bf16 v[58:61], v[58:61], v[54:57], v[74:77]
	s_nop 2
	v_or_b32_e32 v74, 64, v0
	v_cmp_le_i32_e32 vcc, v74, v28
	v_or_b32_e32 v75, 0x41, v0
	s_waitcnt lgkmcnt(0)
	v_mfma_f32_16x16x32_bf16 v[30:33], v[78:81], v[54:57], v[30:33]
	s_waitcnt vmcnt(10)
	v_cndmask_b32_e32 v66, 0, v66, vcc
	v_cmp_le_i32_e32 vcc, v75, v28
	v_or_b32_e32 v75, 0x42, v0
	v_add_u32_e32 v54, v74, v83
	v_cndmask_b32_e32 v67, 0, v67, vcc
	v_cmp_le_i32_e32 vcc, v75, v28
	v_or_b32_e32 v75, 0x43, v0
	v_lshl_add_u32 v54, v54, 1, 0
	v_cndmask_b32_e32 v68, 0, v68, vcc
	v_cmp_le_i32_e32 vcc, v75, v28
	v_or_b32_e32 v75, 0x44, v0
	s_nop 0
	v_cndmask_b32_e32 v69, 0, v69, vcc
	v_cmp_le_i32_e32 vcc, v75, v28
	s_nop 1
	v_cndmask_b32_e32 v75, 0, v62, vcc
	v_or_b32_e32 v62, 0x45, v0
	v_cmp_le_i32_e32 vcc, v62, v28
	v_or_b32_e32 v62, 0x46, v0
	s_nop 0
	v_cndmask_b32_e32 v76, 0, v63, vcc
	v_cmp_le_i32_e32 vcc, v62, v28
	v_or_b32_e32 v62, 0x47, v0
	s_nop 0
	v_cndmask_b32_e32 v77, 0, v64, vcc
	v_cmp_le_i32_e32 vcc, v62, v28
	v_cvt_pk_bf16_f32 v62, v66, v67
	v_mad_u32_u24 v66, v82, s5, v74
	v_lshl_add_u32 v66, v66, 1, 0
	v_cndmask_b32_e32 v65, 0, v65, vcc
	v_cvt_pk_bf16_f32 v63, v68, v69
	v_cvt_pk_bf16_f32 v64, v75, v76
	v_cvt_pk_bf16_f32 v65, v77, v65
	ds_read_b128 v[66:69], v66
	ds_read_b128 v[54:57], v54
	s_waitcnt lgkmcnt(1)
	v_mfma_f32_16x16x32_bf16 v[34:37], v[66:69], v[62:65], v[34:37]
	v_add_u32_e32 v66, v74, v84
	v_lshl_add_u32 v66, v66, 1, 0
	ds_read_b128 v[66:69], v66
	s_waitcnt lgkmcnt(1)
; #define LAS __attribute__((address_space(3)))
; DEV float bflo(unsigned u) { return __uint_as_float(u << 16); }
; DEV float bfhi(unsigned u) { return __uint_as_float(u & 0xffff0000u); }
; DEV unsigned cvt_pk_bf16(float lo, float hi) { unsigned r; asm volatile("v_cvt_pk_bf16_f32 %0, %1, %2" : "=v"(r) : "v"(lo), "v"(hi)); return r; }
; DEV u32x4 pack8(const float (&f)[8]) { u32x4 w; w.x = cvt_pk_bf16(f[0], f[1]); w.y = cvt_pk_bf16(f[2], f[3]); w.z = cvt_pk_bf16(f[4], f[5]); w.w = cvt_pk_bf16(f[6], f[7]); return w; }
; DEV void sgu_item(LAS unsigned char* lds, const bf16_t* P, const bf16_t* VN, const float* sgu_w, const float* sgu_b, bf16_t* OC, int item) {
;     ...
; #pragma unroll
;     for (int ks = 0; ks < 4; ++ks) { const int s0 = ks * 32 + g4 * 8;
;         float wf[8] = {wa[ks][0], wa[ks][1], wa[ks][2], wa[ks][3], wb[ks][0], wb[ks][1], wb[ks][2], wb[ks][3]};
; #pragma unroll
;         for (int j = 0; j < 8; ++j) if (s0 + j > t) wf[j] = 0.f;
;         const bf16x8 wfr = as_bf16x8(pack8(wf));
; #pragma unroll
;         for (int n = 0; n < 8; ++n) { const bf16x8 vf = *(const LAS bf16x8*)(lds + ((n * 16 + fr) * 136 + s0) * 2);
;             acc[n] = __builtin_amdgcn_mfma_f32_16x16x32_bf16(vf, wfr, acc[n], 0, 0, 0); } }
; #pragma unroll
;     for (int n = 0; n < 8; ++n) { const int c = g * 128 + n * 16 + g4 * 4;
;         u32x2 w; w.x = cvt_pk_bf16(bflo(uu[n].x) * (acc[n][0] + bias), bfhi(uu[n].x) * (acc[n][1] + bias)); w.y = cvt_pk_bf16(bflo(uu[n].y) * (acc[n][2] + bias), bfhi(uu[n].y) * (acc[n][3] + bias));
	v_mfma_f32_16x16x32_bf16 v[38:41], v[54:57], v[62:65], v[38:41]
	v_add_u32_e32 v54, v74, v85
	v_lshl_add_u32 v54, v54, 1, 0
	ds_read_b128 v[54:57], v54
	s_waitcnt lgkmcnt(1)
	v_mfma_f32_16x16x32_bf16 v[42:45], v[66:69], v[62:65], v[42:45]
	v_add_u32_e32 v66, v74, v86
	v_lshl_add_u32 v66, v66, 1, 0
	ds_read_b128 v[66:69], v66
	s_waitcnt lgkmcnt(1)
	v_mfma_f32_16x16x32_bf16 v[46:49], v[54:57], v[62:65], v[46:49]
	v_add_u32_e32 v54, v74, v87
	v_lshl_add_u32 v54, v54, 1, 0
	ds_read_b128 v[54:57], v54
	s_waitcnt lgkmcnt(1)
	v_mfma_f32_16x16x32_bf16 v[50:53], v[66:69], v[62:65], v[50:53]
	v_add_u32_e32 v66, v74, v88
	v_lshl_add_u32 v66, v66, 1, 0
	ds_read_b128 v[66:69], v66
	s_waitcnt lgkmcnt(1)
	v_mfma_f32_16x16x32_bf16 v[54:57], v[54:57], v[62:65], v[70:73]
	s_nop 2
	v_add_u32_e32 v70, v74, v89
	v_lshl_add_u32 v70, v70, 1, 0
	ds_read_b128 v[70:73], v70
	s_waitcnt lgkmcnt(1)
	v_mfma_f32_16x16x32_bf16 v[58:61], v[66:69], v[62:65], v[58:61]
	v_or_b32_e32 v66, 0x60, v0
	v_cmp_le_i32_e32 vcc, v66, v28
	v_or_b32_e32 v67, 0x61, v0
	s_waitcnt lgkmcnt(0)
	v_mfma_f32_16x16x32_bf16 v[30:33], v[70:73], v[62:65], v[30:33]
	s_waitcnt vmcnt(8)
	v_cndmask_b32_e32 v6, 0, v6, vcc
	v_cmp_le_i32_e32 vcc, v67, v28
	v_or_b32_e32 v67, 0x62, v0
	s_nop 0
	v_cndmask_b32_e32 v7, 0, v7, vcc
	v_cmp_le_i32_e32 vcc, v67, v28
	v_or_b32_e32 v67, 0x63, v0
	s_nop 0
	v_cndmask_b32_e32 v8, 0, v8, vcc
	v_cmp_le_i32_e32 vcc, v67, v28
	v_or_b32_e32 v67, 0x64, v0
	s_nop 0
	v_cndmask_b32_e32 v9, 0, v9, vcc
	v_cmp_le_i32_e32 vcc, v67, v28
	s_nop 1
	v_cndmask_b32_e32 v67, 0, v2, vcc
	v_or_b32_e32 v2, 0x65, v0
	v_cmp_le_i32_e32 vcc, v2, v28
	v_or_b32_e32 v2, 0x66, v0
	s_nop 0
	v_cndmask_b32_e32 v68, 0, v3, vcc
	v_cmp_le_i32_e32 vcc, v2, v28
	v_or_b32_e32 v2, 0x67, v0
	v_or_b32_e32 v0, s4, v0
	v_cndmask_b32_e32 v69, 0, v4, vcc
	v_cmp_le_i32_e32 vcc, v2, v28
	v_cvt_pk_bf16_f32 v2, v6, v7
	v_mad_u32_u24 v6, v82, s5, v66
	v_lshl_add_u32 v6, v6, 1, 0
	v_cndmask_b32_e32 v5, 0, v5, vcc
	v_cvt_pk_bf16_f32 v3, v8, v9
	v_cvt_pk_bf16_f32 v4, v67, v68
	v_cvt_pk_bf16_f32 v5, v69, v5
	ds_read_b128 v[6:9], v6
	v_add_u32_e32 v28, v66, v83
	v_lshl_add_u32 v28, v28, 1, 0
	ds_read_b128 v[62:65], v28
	v_add_u32_e32 v28, v66, v84
	v_lshl_add_u32 v28, v28, 1, 0
	s_waitcnt lgkmcnt(1)
	v_mfma_f32_16x16x32_bf16 v[6:9], v[6:9], v[2:5], v[34:37]
	s_nop 2
	ds_read_b128 v[34:37], v28
	v_add_u32_e32 v28, v66, v85
	v_lshl_add_u32 v28, v28, 1, 0
	s_waitcnt lgkmcnt(1)
	v_mfma_f32_16x16x32_bf16 v[38:41], v[62:65], v[2:5], v[38:41]
	ds_read_b128 v[62:65], v28
	v_add_u32_e32 v28, v66, v86
	v_lshl_add_u32 v28, v28, 1, 0
	s_waitcnt lgkmcnt(1)
	v_mfma_f32_16x16x32_bf16 v[34:37], v[34:37], v[2:5], v[42:45]
	v_add_f32_e32 v6, v29, v6
	s_nop 1
	ds_read_b128 v[42:45], v28
	v_add_u32_e32 v28, v66, v87
	v_lshl_add_u32 v28, v28, 1, 0
	s_waitcnt lgkmcnt(1)
	v_mfma_f32_16x16x32_bf16 v[46:49], v[62:65], v[2:5], v[46:49]
	ds_read_b128 v[62:65], v28
	v_add_u32_e32 v28, v66, v88
	v_lshl_add_u32 v28, v28, 1, 0
	s_waitcnt lgkmcnt(1)
	v_mfma_f32_16x16x32_bf16 v[42:45], v[42:45], v[2:5], v[50:53]
	v_add_f32_e32 v7, v29, v7
	s_nop 1
	ds_read_b128 v[50:53], v28
	v_add_u32_e32 v28, v66, v89
	v_lshl_add_u32 v28, v28, 1, 0
	s_waitcnt lgkmcnt(1)
	v_mfma_f32_16x16x32_bf16 v[54:57], v[62:65], v[2:5], v[54:57]
	ds_read_b128 v[62:65], v28
	s_waitcnt vmcnt(3)
; DEV float bflo(unsigned u) { return __uint_as_float(u << 16); }
; DEV float bfhi(unsigned u) { return __uint_as_float(u & 0xffff0000u); }
; DEV unsigned cvt_pk_bf16(float lo, float hi) { unsigned r; asm volatile("v_cvt_pk_bf16_f32 %0, %1, %2" : "=v"(r) : "v"(lo), "v"(hi)); return r; }
; DEV void sgu_item(LAS unsigned char* lds, const bf16_t* P, const bf16_t* VN, const float* sgu_w, const float* sgu_b, bf16_t* OC, int item) {
;     ...
; #pragma unroll
;     for (int n = 0; n < 8; ++n) { const int c = g * 128 + n * 16 + g4 * 4;
;         u32x2 w; w.x = cvt_pk_bf16(bflo(uu[n].x) * (acc[n][0] + bias), bfhi(uu[n].x) * (acc[n][1] + bias)); w.y = cvt_pk_bf16(bflo(uu[n].y) * (acc[n][2] + bias), bfhi(uu[n].y) * (acc[n][3] + bias));
;         *(u32x2*)(OC + tok * 1024 + c) = w; }
	v_lshlrev_b32_e32 v28, 16, v26
	v_and_b32_e32 v26, 0xffff0000, v26
	v_mul_f32_e32 v6, v6, v28
	v_mul_f32_e32 v7, v7, v26
	v_cvt_pk_bf16_f32 v104, v6, v7
	v_lshlrev_b32_e32 v7, 16, v27
	v_add_f32_e32 v8, v29, v8
	v_mul_f32_e32 v7, v8, v7
	v_and_b32_e32 v8, 0xffff0000, v27
	v_add_f32_e32 v9, v29, v9
	v_mul_f32_e32 v8, v9, v8
	v_cvt_pk_bf16_f32 v105, v7, v8
	v_lshl_add_u64 v[8:9], v[24:25], 0, v[0:1]
	v_and_b32_e32 v120, 16, v213
	v_lshrrev_b32_e32 v121, 1, v120
	v_add_u32_e32 v120, v120, v121
	v_add_co_u32_e32 v8, vcc, v8, v120
	s_nop 1
	v_addc_co_u32_e32 v9, vcc, 0, v9, vcc
	v_lshlrev_b32_e32 v0, 16, v22
	v_add_f32_e32 v6, v29, v38
	v_mul_f32_e32 v0, v6, v0
	v_and_b32_e32 v6, 0xffff0000, v22
	v_add_f32_e32 v7, v29, v39
	v_mul_f32_e32 v6, v7, v6
	v_cvt_pk_bf16_f32 v106, v0, v6
	v_lshlrev_b32_e32 v0, 16, v23
	v_add_f32_e32 v7, v29, v40
	v_mul_f32_e32 v0, v7, v0
	v_and_b32_e32 v7, 0xffff0000, v23
	v_add_f32_e32 v22, v29, v41
	v_mul_f32_e32 v7, v22, v7
	v_cvt_pk_bf16_f32 v107, v0, v7
	s_nop 1
	v_permlane16_swap_b32_e32 v104, v106
	v_permlane16_swap_b32_e32 v105, v107
	global_store_dwordx4 v[8:9], v[104:107], off
	v_lshlrev_b32_e32 v0, 16, v20
	v_add_f32_e32 v6, v29, v34
	v_mul_f32_e32 v0, v6, v0
	v_and_b32_e32 v6, 0xffff0000, v20
	v_add_f32_e32 v7, v29, v35
	v_mul_f32_e32 v6, v7, v6
	v_cvt_pk_bf16_f32 v108, v0, v6
	v_lshlrev_b32_e32 v0, 16, v21
	v_add_f32_e32 v7, v29, v36
	v_mul_f32_e32 v0, v7, v0
	v_and_b32_e32 v7, 0xffff0000, v21
	v_add_f32_e32 v20, v29, v37
	v_mul_f32_e32 v7, v20, v7
	v_cvt_pk_bf16_f32 v109, v0, v7
	v_lshlrev_b32_e32 v0, 16, v18
	v_add_f32_e32 v6, v29, v46
	v_mul_f32_e32 v0, v6, v0
	v_and_b32_e32 v6, 0xffff0000, v18
	v_add_f32_e32 v7, v29, v47
	v_mul_f32_e32 v6, v7, v6
	v_cvt_pk_bf16_f32 v110, v0, v6
	v_lshlrev_b32_e32 v0, 16, v19
	v_add_f32_e32 v7, v29, v48
	v_mul_f32_e32 v0, v7, v0
	v_and_b32_e32 v7, 0xffff0000, v19
	v_add_f32_e32 v18, v29, v49
	v_mul_f32_e32 v7, v18, v7
	v_cvt_pk_bf16_f32 v111, v0, v7
	s_nop 1
	v_permlane16_swap_b32_e32 v108, v110
	v_permlane16_swap_b32_e32 v109, v111
	global_store_dwordx4 v[8:9], v[108:111], off offset:64
	v_lshlrev_b32_e32 v0, 16, v16
	v_add_f32_e32 v6, v29, v42
	v_mul_f32_e32 v0, v6, v0
	v_and_b32_e32 v6, 0xffff0000, v16
	v_add_f32_e32 v7, v29, v43
	v_mul_f32_e32 v6, v7, v6
	v_cvt_pk_bf16_f32 v112, v0, v6
	v_lshlrev_b32_e32 v0, 16, v17
	v_add_f32_e32 v7, v29, v44
	v_mul_f32_e32 v0, v7, v0
	v_and_b32_e32 v7, 0xffff0000, v17
	v_add_f32_e32 v16, v29, v45
	v_mul_f32_e32 v7, v16, v7
	v_cvt_pk_bf16_f32 v113, v0, v7
	s_waitcnt vmcnt(4)
	v_lshlrev_b32_e32 v0, 16, v14
	v_add_f32_e32 v6, v29, v54
	v_mul_f32_e32 v0, v6, v0
	v_and_b32_e32 v6, 0xffff0000, v14
	v_add_f32_e32 v7, v29, v55
	s_waitcnt lgkmcnt(1)
	v_mfma_f32_16x16x32_bf16 v[50:53], v[50:53], v[2:5], v[58:61]
	v_mul_f32_e32 v6, v7, v6
	v_cvt_pk_bf16_f32 v114, v0, v6
	v_lshlrev_b32_e32 v0, 16, v15
	v_add_f32_e32 v7, v29, v56
	v_mul_f32_e32 v0, v7, v0
	v_and_b32_e32 v7, 0xffff0000, v15
	v_add_f32_e32 v14, v29, v57
	v_mul_f32_e32 v7, v14, v7
	v_cvt_pk_bf16_f32 v115, v0, v7
	s_nop 1
	v_permlane16_swap_b32_e32 v112, v114
	v_permlane16_swap_b32_e32 v113, v115
	global_store_dwordx4 v[8:9], v[112:115], off offset:128
	s_waitcnt vmcnt(4)
	v_lshlrev_b32_e32 v0, 16, v12
	v_add_f32_e32 v6, v29, v50
	v_mul_f32_e32 v0, v6, v0
	v_and_b32_e32 v6, 0xffff0000, v12
	v_add_f32_e32 v7, v29, v51
	s_waitcnt lgkmcnt(0)
	v_mfma_f32_16x16x32_bf16 v[2:5], v[62:65], v[2:5], v[30:33]
	v_mul_f32_e32 v6, v7, v6
	v_cvt_pk_bf16_f32 v116, v0, v6
	v_lshlrev_b32_e32 v0, 16, v13
	v_add_f32_e32 v7, v29, v52
	v_mul_f32_e32 v0, v7, v0
	v_and_b32_e32 v7, 0xffff0000, v13
	v_add_f32_e32 v12, v29, v53
	v_mul_f32_e32 v7, v12, v7
	v_cvt_pk_bf16_f32 v117, v0, v7
	s_waitcnt vmcnt(3)
	v_lshlrev_b32_e32 v0, 16, v10
	v_add_f32_e32 v2, v29, v2
	v_mul_f32_e32 v0, v2, v0
	v_and_b32_e32 v2, 0xffff0000, v10
	v_add_f32_e32 v3, v29, v3
	v_mul_f32_e32 v2, v3, v2
	v_cvt_pk_bf16_f32 v118, v0, v2
	v_lshlrev_b32_e32 v0, 16, v11
	v_add_f32_e32 v3, v29, v4
	v_mul_f32_e32 v0, v3, v0
	v_and_b32_e32 v3, 0xffff0000, v11
	v_add_f32_e32 v4, v29, v5
	v_mul_f32_e32 v3, v4, v3
	v_cvt_pk_bf16_f32 v119, v0, v3
	s_nop 1
	v_permlane16_swap_b32_e32 v116, v118
	v_permlane16_swap_b32_e32 v117, v119
	global_store_dwordx4 v[8:9], v[116:119], off offset:192
	s_barrier
	s_mov_b64 s[4:5], 0
